# forgetting-attention key loop: iterations whose two half-steps are on the full path run as one straight block chosen by a scalar test at the loop top (no per-lane exec-mask tests)
# speedup vs baseline: 1.0099x; 1.0099x over previous
.LBB0_683:
	s_and_b64 vcc, exec, s[74:75]
	s_mov_b32 s12, 0
	s_waitcnt lgkmcnt(0)
	s_barrier
	s_cbranch_vccnz .LBB0_735
	s_cmp_lg_u32 0x100, -1
	s_cselect_b32 s12, 0x100, 0
	s_add_i32 s14, s12, 0x3800
	s_addk_i32 s12, 0x2000
	v_add_u32_e32 v168, s12, v156
	s_lshl_b32 s12, s3, 2
	s_add_i32 s82, s82, s12
	s_mov_b32 s92, 0
	v_add_u32_e32 v167, s14, v156
	v_or_b32_e32 v169, 1, v157
	v_mov_b32_e32 v33, v32
	v_mov_b32_e32 v82, v32
	v_mov_b32_e32 v83, v32
	v_mov_b32_e32 v84, v32
	v_mov_b32_e32 v85, v32
	v_mov_b32_e32 v86, v32
	v_mov_b32_e32 v87, v32
	v_mov_b32_e32 v88, v32
	v_mov_b32_e32 v89, v32
	v_mov_b32_e32 v90, v32
	v_mov_b32_e32 v91, v32
	v_mov_b32_e32 v92, v32
	v_mov_b32_e32 v93, v32
	v_mov_b32_e32 v94, v32
	s_add_i32 s14, s76, 0x80
	s_sub_i32 s93, 0, s82
	s_mov_b32 s97, 0xa200
	s_movk_i32 s15, 0x5100
	s_mov_b32 s82, 3
	s_movk_i32 s83, 0xfe01
	v_mov_b32_e32 v95, v32
	v_lshl_add_u32 v182, v150, 1, v152
	v_readfirstlane_b32 s98, v157
.LBB0_685:
	s_add_i32 s12, s82, -1
	s_cmp_lt_i32 s12, s98
	s_cbranch_scc0 .LfB_generic
	s_add_i32 s12, s83, 0x202
	s_cmp_lt_i32 s12, s9
	s_cbranch_scc1 .LfB_iter

.LfB_iter:
	s_mov_b32 s12, s15
	s_add_i32 s18, s14, 64
	s_ashr_i32 s19, s18, 31
	s_lshl_b64 s[20:21], s[18:19], 13
	s_add_u32 s15, s10, s20
	s_addc_u32 s21, s11, s21
	s_add_u32 s20, s15, s8
	s_addc_u32 s21, s21, 0
	s_add_u32 s20, s20, 0x1000
	s_addc_u32 s21, s21, 0
	v_mov_b32_e32 v153, v0
	global_load_dwordx4 v[136:139], v182, s[20:21] offset:1024
	s_and_saveexec_b64 s[20:21], s[6:7]
	s_cbranch_execz .LfB_688
	v_lshl_add_u64 v[2:3], s[18:19], 2, v[154:155]
	global_load_dwordx4 v[128:131], v[2:3], off
.LfB_688:
	s_or_b64 exec, exec, s[20:21]
	s_ashr_i32 s15, s14, 31
	s_lshl_b64 s[20:21], s[14:15], 13
	s_add_u32 s20, s95, s20
	s_addc_u32 s21, s96, s21
	s_add_u32 s20, s20, 0x1000
	s_addc_u32 s21, s21, 0
	v_mov_b32_e32 v153, v0
	global_load_dwordx4 v[132:135], v182, s[20:21] offset:2048
	s_add_i32 s15, s12, 0x100
	v_add_u32_e32 v1, s15, v148
	s_waitcnt lgkmcnt(0)
	ds_read_b128 v[174:177], v1 offset:20704
	ds_read_b128 v[178:181], v1 offset:20672
	ds_read_b128 v[248:251], v1 offset:20640
	ds_read_b128 v[252:255], v1 offset:20608
	v_add_u32_e32 v153, s92, v167
	v_add_u32_e32 v1, s15, v162
	v_add_u32_e32 v10, v1, v163
	v_add_u32_e32 v14, v1, v164
	v_add_u32_e32 v15, v1, v165
	v_add_u32_e32 v1, v1, v166
	ds_read_b64_tr_b16 v[2:3], v153
	ds_read_b64_tr_b16 v[4:5], v153 offset:1536
	ds_read_b64_tr_b16 v[8:9], v153 offset:1600
	ds_read_b64_tr_b16 v[6:7], v153 offset:64
	ds_read_b128 v[10:13], v10 offset:4096
	ds_read_b128 v[104:107], v14 offset:4096
	ds_read_b128 v[108:111], v15 offset:4096
	ds_read_b128 v[140:143], v1 offset:4096
	s_waitcnt lgkmcnt(11)
	v_sub_f32_e32 v49, v95, v177
	v_sub_f32_e32 v48, v94, v176
	v_sub_f32_e32 v47, v93, v175
	v_sub_f32_e32 v46, v92, v174
	s_waitcnt lgkmcnt(10)
	v_sub_f32_e32 v45, v91, v181
	v_sub_f32_e32 v44, v90, v180
	v_sub_f32_e32 v43, v89, v179
	v_sub_f32_e32 v42, v88, v178
	s_waitcnt lgkmcnt(9)
	v_sub_f32_e32 v41, v87, v251
	v_sub_f32_e32 v40, v86, v250
	v_sub_f32_e32 v39, v85, v249
	v_sub_f32_e32 v38, v84, v248
	s_waitcnt lgkmcnt(8)
	v_sub_f32_e32 v37, v83, v255
	v_sub_f32_e32 v36, v82, v254
	v_sub_f32_e32 v35, v33, v253
	v_sub_f32_e32 v34, v32, v252
	s_nop 1
	s_setprio 1
	s_waitcnt lgkmcnt(3)
	v_mfma_f32_32x32x16_bf16 v[34:49], v[10:13], v[120:123], v[34:49]
	v_exp_f32_e32 v14, v72
	v_exp_f32_e32 v15, v80
	s_waitcnt lgkmcnt(2)
	v_mfma_f32_32x32x16_bf16 v[34:49], v[104:107], v[112:115], v[34:49]
	ds_read_b64_tr_b16 v[10:11], v153 offset:3072
	ds_read_b64_tr_b16 v[12:13], v153 offset:4608
	ds_read_b64_tr_b16 v[104:105], v153 offset:3136
	ds_read_b64_tr_b16 v[106:107], v153 offset:4672
	v_mfma_f32_32x32x16_bf16 v[50:65], v[2:5], v[96:99], v[50:65]
	v_exp_f32_e32 v2, v66
	v_exp_f32_e32 v4, v67
	v_exp_f32_e32 v3, v74
	v_exp_f32_e32 v5, v75
	v_mfma_f32_32x32x16_bf16 v[16:31], v[6:9], v[96:99], v[16:31]
	v_exp_f32_e32 v6, v68
	v_exp_f32_e32 v8, v69
	v_exp_f32_e32 v7, v76
	v_exp_f32_e32 v9, v77
	s_waitcnt lgkmcnt(5)
	v_mfma_f32_32x32x16_bf16 v[34:49], v[108:111], v[116:119], v[34:49]
	s_waitcnt lgkmcnt(2)
	v_mfma_f32_32x32x16_bf16 v[50:65], v[10:13], v[100:103], v[50:65]
	v_exp_f32_e32 v10, v70
	v_exp_f32_e32 v12, v71
	v_exp_f32_e32 v11, v78
	v_exp_f32_e32 v13, v79
	s_waitcnt lgkmcnt(0)
	v_mfma_f32_32x32x16_bf16 v[16:31], v[104:107], v[100:103], v[16:31]
	v_exp_f32_e32 v102, v73
	v_exp_f32_e32 v103, v81
	v_add_f32_e32 v1, v14, v15
	v_add_f32_e32 v1, v1, v2
	v_add_f32_e32 v1, v1, v4
	v_add_f32_e32 v1, v1, v3
	v_add_f32_e32 v1, v1, v5
	v_add_f32_e32 v1, v1, v6
	v_add_f32_e32 v1, v1, v8
	v_add_f32_e32 v1, v1, v7
	v_add_f32_e32 v1, v1, v9
	v_add_f32_e32 v1, v1, v10
	v_add_f32_e32 v1, v1, v12
	v_add_f32_e32 v1, v1, v11
	v_add_f32_e32 v1, v1, v13
	v_add_f32_e32 v1, v1, v102
	v_add_f32_e32 v1, v1, v103
	v_add_f32_e32 v160, v160, v1
	v_mfma_f32_32x32x16_bf16 v[34:49], v[140:143], v[124:127], v[34:49]
	v_cvt_pk_bf16_f32 v98, v10, v12
	v_cvt_pk_bf16_f32 v96, v2, v4
	v_cvt_pk_bf16_f32 v97, v6, v8
	v_cvt_pk_bf16_f32 v99, v14, v102
	v_cvt_pk_bf16_f32 v100, v3, v5
	v_cvt_pk_bf16_f32 v101, v7, v9
	v_cvt_pk_bf16_f32 v102, v11, v13
	v_cvt_pk_bf16_f32 v103, v15, v103
	s_setprio 0
	s_add_i32 s15, s97, 0x100
	v_add_u32_e32 v1, s15, v148
	s_waitcnt lgkmcnt(0)
	ds_read_b128 v[174:177], v1 offset:20576
	ds_read_b128 v[178:181], v1 offset:20544
	ds_read_b128 v[248:251], v1 offset:20512
	ds_read_b128 v[252:255], v1 offset:20480
	v_add_u32_e32 v153, s12, v168
	v_add_u32_e32 v1, s15, v162
	v_add_u32_e32 v10, v1, v163
	v_add_u32_e32 v14, v1, v164
	v_add_u32_e32 v15, v1, v165
	v_add_u32_e32 v1, v1, v166
	ds_read_b64_tr_b16 v[2:3], v153
	ds_read_b64_tr_b16 v[4:5], v153 offset:1536
	ds_read_b64_tr_b16 v[8:9], v153 offset:1600
	ds_read_b64_tr_b16 v[6:7], v153 offset:64
	ds_read_b128 v[10:13], v10
	ds_read_b128 v[104:107], v14
	ds_read_b128 v[108:111], v15
	ds_read_b128 v[140:143], v1
	s_waitcnt lgkmcnt(11)
	v_sub_f32_e32 v81, v95, v177
	v_sub_f32_e32 v80, v94, v176
	v_sub_f32_e32 v79, v93, v175
	v_sub_f32_e32 v78, v92, v174
	s_waitcnt lgkmcnt(10)
	v_sub_f32_e32 v77, v91, v181
	v_sub_f32_e32 v76, v90, v180
	v_sub_f32_e32 v75, v89, v179
	v_sub_f32_e32 v74, v88, v178
	s_waitcnt lgkmcnt(9)
	v_sub_f32_e32 v73, v87, v251
	v_sub_f32_e32 v72, v86, v250
	v_sub_f32_e32 v71, v85, v249
	v_sub_f32_e32 v70, v84, v248
	s_waitcnt lgkmcnt(8)
	v_sub_f32_e32 v69, v83, v255
	v_sub_f32_e32 v68, v82, v254
	v_sub_f32_e32 v67, v33, v253
	v_sub_f32_e32 v66, v32, v252
	s_nop 1
	s_setprio 1
	s_waitcnt lgkmcnt(3)
	v_mfma_f32_32x32x16_bf16 v[66:81], v[10:13], v[120:123], v[66:81]
	v_exp_f32_e32 v14, v40
	v_exp_f32_e32 v15, v48
	s_waitcnt lgkmcnt(2)
	v_mfma_f32_32x32x16_bf16 v[66:81], v[104:107], v[112:115], v[66:81]
	ds_read_b64_tr_b16 v[10:11], v153 offset:3072
	ds_read_b64_tr_b16 v[12:13], v153 offset:4608
	ds_read_b64_tr_b16 v[104:105], v153 offset:3136
	ds_read_b64_tr_b16 v[106:107], v153 offset:4672
	v_mfma_f32_32x32x16_bf16 v[50:65], v[2:5], v[96:99], v[50:65]
	v_exp_f32_e32 v2, v34
	v_exp_f32_e32 v4, v35
	v_exp_f32_e32 v3, v42
	v_exp_f32_e32 v5, v43
	v_mfma_f32_32x32x16_bf16 v[16:31], v[6:9], v[96:99], v[16:31]
	v_exp_f32_e32 v6, v36
	v_exp_f32_e32 v8, v37
	v_exp_f32_e32 v7, v44
	v_exp_f32_e32 v9, v45
	s_waitcnt lgkmcnt(5)
	v_mfma_f32_32x32x16_bf16 v[66:81], v[108:111], v[116:119], v[66:81]
	s_waitcnt lgkmcnt(2)
	v_mfma_f32_32x32x16_bf16 v[50:65], v[10:13], v[100:103], v[50:65]
	v_exp_f32_e32 v10, v38
	v_exp_f32_e32 v12, v39
	v_exp_f32_e32 v11, v46
	v_exp_f32_e32 v13, v47
	s_waitcnt lgkmcnt(0)
	v_mfma_f32_32x32x16_bf16 v[16:31], v[104:107], v[100:103], v[16:31]
	v_exp_f32_e32 v102, v41
	v_exp_f32_e32 v103, v49
	v_add_f32_e32 v1, v14, v15
	v_add_f32_e32 v1, v1, v2
	v_add_f32_e32 v1, v1, v4
	v_add_f32_e32 v1, v1, v3
	v_add_f32_e32 v1, v1, v5
	v_add_f32_e32 v1, v1, v6
	v_add_f32_e32 v1, v1, v8
	v_add_f32_e32 v1, v1, v7
	v_add_f32_e32 v1, v1, v9
	v_add_f32_e32 v1, v1, v10
	v_add_f32_e32 v1, v1, v12
	v_add_f32_e32 v1, v1, v11
	v_add_f32_e32 v1, v1, v13
	v_add_f32_e32 v1, v1, v102
	v_add_f32_e32 v1, v1, v103
	v_add_f32_e32 v160, v160, v1
	v_mfma_f32_32x32x16_bf16 v[66:81], v[140:143], v[124:127], v[66:81]
	v_cvt_pk_bf16_f32 v98, v10, v12
	v_cvt_pk_bf16_f32 v96, v2, v4
	v_cvt_pk_bf16_f32 v97, v6, v8
	v_cvt_pk_bf16_f32 v99, v14, v102
	v_cvt_pk_bf16_f32 v100, v3, v5
	v_cvt_pk_bf16_f32 v101, v7, v9
	v_cvt_pk_bf16_f32 v102, v11, v13
	v_cvt_pk_bf16_f32 v103, v15, v103
	s_setprio 0
	s_add_i32 s15, s92, 0x100
	v_add_u32_e32 v1, s15, v159
	s_waitcnt vmcnt(0)
	ds_write_b128 v1, v[136:139]
	s_and_saveexec_b64 s[16:17], s[6:7]
	s_cbranch_execz .LfB_734
	s_mov_b32 s20, 0x3fb8aa3b
	v_add_u32_e32 v1, s15, v158
	s_waitcnt lgkmcnt(1)
	v_pk_mul_f32 v[4:5], v[130:131], s[20:21] op_sel_hi:[1,0]
	s_mov_b32 s90, 0x3fb8aa3b
	v_pk_mul_f32 v[2:3], v[128:129], s[20:21] op_sel_hi:[1,0]
	ds_write_b128 v1, v[2:5] offset:20480
.LfB_734:
	s_or_b64 exec, exec, s[16:17]
	v_add_u32_e32 v1, s97, v161
	s_waitcnt vmcnt(0)
	ds_write_b128 v1, v[132:135] offset:8192
	s_add_i32 s82, s82, 2
	s_add_i32 s14, s14, 64
	s_add_i32 s83, s83, 1
	s_cmp_eq_u32 s93, s83
	s_waitcnt lgkmcnt(0)
	s_barrier
	s_cbranch_scc1 .LBB0_735
	s_mov_b32 s15, s97
	s_mov_b32 s97, s92
	s_mov_b32 s92, s12
	s_branch .LBB0_685
